# DMA version + all 8 K-fragment LDS reads issued up-front per half-step (distinct registers, counted lgkmcnt)
# speedup vs baseline: 1.0019x; 1.0019x over previous
.LBB0_398:
	ds_read_b128 v[222:225], v208 offset:40960
	ds_read_b128 v[230:233], v209 offset:40960
	ds_read_b128 v[150:153], v210 offset:40960
	ds_read_b128 v[160:163], v211 offset:40960
	ds_read_b128 v[226:229], v208 offset:45056
	ds_read_b128 v[182:185], v209 offset:45056
	ds_read_b128 v[234:237], v210 offset:45056
	ds_read_b128 v[218:221], v211 offset:45056
	v_exp_f32_e32 v148, v80
	v_exp_f32_e32 v149, v81
	s_waitcnt lgkmcnt(7)
	v_mfma_f32_32x32x16_bf16 v[112:127], v[222:225], v[64:67], v[96:111]
	v_exp_f32_e32 v154, v84
	v_exp_f32_e32 v155, v85
	v_exp_f32_e32 v158, v86
	v_exp_f32_e32 v159, v87
	v_exp_f32_e32 v156, v90
	v_exp_f32_e32 v157, v91
	s_waitcnt lgkmcnt(6)
	v_mfma_f32_32x32x16_bf16 v[112:127], v[230:233], v[68:71], v[112:127]
	v_exp_f32_e32 v166, v94
	v_exp_f32_e32 v167, v95
	s_waitcnt lgkmcnt(5)
	v_mfma_f32_32x32x16_bf16 v[112:127], v[150:153], v[72:75], v[112:127]
	v_exp_f32_e32 v152, v82
	v_exp_f32_e32 v153, v83
	v_exp_f32_e32 v150, v88
	v_exp_f32_e32 v151, v89
	s_waitcnt lgkmcnt(4)
	v_mfma_f32_32x32x16_bf16 v[112:127], v[160:163], v[76:79], v[112:127]
	v_exp_f32_e32 v162, v92
	v_exp_f32_e32 v163, v93
	s_waitcnt lgkmcnt(3)
	v_mfma_f32_32x32x16_bf16 v[80:95], v[226:229], v[64:67], v[96:111]
	v_add_f32_e32 v238, v164, v148
	v_add_f32_e32 v238, v149, v238
	v_add_f32_e32 v238, v152, v238
	v_add_f32_e32 v238, v153, v238
	v_add_f32_e32 v238, v154, v238
	v_add_f32_e32 v238, v155, v238
	v_add_f32_e32 v238, v158, v238
	s_waitcnt lgkmcnt(2)
	v_mfma_f32_32x32x16_bf16 v[80:95], v[182:185], v[68:71], v[80:95]
	v_add_f32_e32 v238, v159, v238
	v_add_f32_e32 v238, v150, v238
	v_add_f32_e32 v238, v151, v238
	v_add_f32_e32 v238, v156, v238
	v_add_f32_e32 v238, v157, v238
	v_add_f32_e32 v238, v162, v238
	v_add_f32_e32 v238, v163, v238
	s_waitcnt lgkmcnt(1)
	v_mfma_f32_32x32x16_bf16 v[80:95], v[234:237], v[72:75], v[80:95]
	v_add_f32_e32 v239, v166, v238
	v_add_f32_e32 v239, v167, v239
	v_mov_b32_e32 v240, v239
	s_nop 1
	v_permlane32_swap_b32_e32 v239, v240
	v_add_f32_e32 v164, v239, v240
	v_cmp_ge_f32_e32 vcc, s99, v164
	s_waitcnt lgkmcnt(0)
	v_mfma_f32_32x32x16_bf16 v[80:95], v[218:221], v[76:79], v[80:95]
	s_cmp_eq_u64 vcc, exec
	s_cbranch_scc0 .LBB0_405
.LBB0_400:
	v_cvt_pk_bf16_f32 v182, v148, v149
	v_cvt_pk_bf16_f32 v183, v152, v153
	v_cvt_pk_bf16_f32 v184, v154, v155
	v_cvt_pk_bf16_f32 v185, v158, v159
	v_cvt_pk_bf16_f32 v160, v150, v151
	v_cvt_pk_bf16_f32 v161, v156, v157
	v_cvt_pk_bf16_f32 v162, v162, v163
	v_cvt_pk_bf16_f32 v163, v166, v167
	s_cmpk_lt_u32 s51, 0x100
	s_cselect_b32 s0, s38, s34
	s_add_i32 s3, s0, s51
	s_mul_i32 s0, s3, 0x1800
	s_mul_hi_i32 s1, s3, 0x1800
	s_add_u32 s0, s39, s0
	s_addc_u32 s1, s42, s1
	s_max_i32 vcc_lo, s100, 0
	s_add_i32 vcc_lo, vcc_lo, s96
	s_add_i32 m0, vcc_lo, 0x4100
	s_nop 0
	global_load_lds_dwordx4 v129, s[0:1]
	s_add_i32 m0, vcc_lo, 0x4500
	s_nop 0
	global_load_lds_dwordx4 v130, s[0:1]
	s_mul_i32 s0, s3, 0x1800
	s_mul_hi_i32 s1, s3, 0x1800
	s_add_u32 s0, s28, s0
	s_addc_u32 s1, s29, s1
	s_max_i32 vcc_lo, s101, 0
	s_add_i32 vcc_lo, vcc_lo, s97
	s_add_i32 m0, vcc_lo, 0xa100
	s_nop 0
	global_load_lds_dwordx4 v128, s[0:1]
	ds_read_b64_tr_b16 v[186:187], v203 offset:0
	ds_read_b64_tr_b16 v[188:189], v203 offset:0x800
	ds_read_b64_tr_b16 v[214:215], v203 offset:0x200
	ds_read_b64_tr_b16 v[216:217], v203 offset:0xa00
	ds_read_b64_tr_b16 v[218:219], v203 offset:0x400
	ds_read_b64_tr_b16 v[220:221], v203 offset:0xc00
	ds_read_b64_tr_b16 v[222:223], v203 offset:0x600
	ds_read_b64_tr_b16 v[224:225], v203 offset:0xe00
	ds_read_b64_tr_b16 v[226:227], v203 offset:0x1000
	ds_read_b64_tr_b16 v[228:229], v203 offset:0x1800
	ds_read_b64_tr_b16 v[230:231], v203 offset:0x1200
	ds_read_b64_tr_b16 v[232:233], v203 offset:0x1a00
	ds_read_b64_tr_b16 v[234:235], v203 offset:0x1400
	ds_read_b64_tr_b16 v[236:237], v203 offset:0x1c00
	ds_read_b64_tr_b16 v[238:239], v203 offset:0x1600
	ds_read_b64_tr_b16 v[240:241], v203 offset:0x1e00
	s_nop 0
	s_waitcnt lgkmcnt(8)
	v_exp_f32_e32 v112, v112
	v_mfma_f32_32x32x16_bf16 v[0:15], v[144:147], v[186:189], v[0:15]
	v_exp_f32_e32 v113, v113
	v_exp_f32_e32 v114, v114
	v_exp_f32_e32 v115, v115
	v_exp_f32_e32 v116, v116
	v_exp_f32_e32 v117, v117
	v_exp_f32_e32 v118, v118
	v_exp_f32_e32 v119, v119
	v_mfma_f32_32x32x16_bf16 v[48:63], v[144:147], v[214:217], v[48:63]
	v_exp_f32_e32 v120, v120
	v_exp_f32_e32 v121, v121
	v_exp_f32_e32 v122, v122
	v_exp_f32_e32 v123, v123
	v_exp_f32_e32 v124, v124
	v_exp_f32_e32 v125, v125
	v_exp_f32_e32 v126, v126
	v_mfma_f32_32x32x16_bf16 v[32:47], v[144:147], v[218:221], v[32:47]
	v_exp_f32_e32 v127, v127
	v_mfma_f32_32x32x16_bf16 v[16:31], v[144:147], v[222:225], v[16:31]
	ds_read_b64_tr_b16 v[144:145], v203 offset:0x2000
	ds_read_b64_tr_b16 v[146:147], v203 offset:0x2800
	ds_read_b64_tr_b16 v[186:187], v203 offset:0x2200
	ds_read_b64_tr_b16 v[188:189], v203 offset:0x2a00
	ds_read_b64_tr_b16 v[214:215], v203 offset:0x2400
	ds_read_b64_tr_b16 v[216:217], v203 offset:0x2c00
	ds_read_b64_tr_b16 v[218:219], v203 offset:0x2600
	ds_read_b64_tr_b16 v[220:221], v203 offset:0x2e00
	s_waitcnt lgkmcnt(8)
	ds_read_b64_tr_b16 v[222:223], v203 offset:0x3000
	ds_read_b64_tr_b16 v[224:225], v203 offset:0x3800
	s_nop 0
	v_mfma_f32_32x32x16_bf16 v[0:15], v[140:143], v[226:229], v[0:15]
	ds_read_b64_tr_b16 v[226:227], v203 offset:0x3200
	ds_read_b64_tr_b16 v[228:229], v203 offset:0x3a00
	v_mfma_f32_32x32x16_bf16 v[48:63], v[140:143], v[230:233], v[48:63]
	ds_read_b64_tr_b16 v[230:231], v203 offset:0x3400
	ds_read_b64_tr_b16 v[232:233], v203 offset:0x3c00
	v_mfma_f32_32x32x16_bf16 v[32:47], v[140:143], v[234:237], v[32:47]
	ds_read_b64_tr_b16 v[234:235], v203 offset:0x3600
	ds_read_b64_tr_b16 v[236:237], v203 offset:0x3e00
	s_waitcnt lgkmcnt(8)
	s_nop 0
	s_waitcnt lgkmcnt(0)
	v_mfma_f32_32x32x16_bf16 v[16:31], v[140:143], v[238:241], v[16:31]
	v_add_f32_e32 v140, 0, v112
	v_add_f32_e32 v140, v113, v140
	v_add_f32_e32 v140, v114, v140
	v_add_f32_e32 v140, v115, v140
	v_add_f32_e32 v140, v116, v140
	v_add_f32_e32 v140, v117, v140
	v_add_f32_e32 v140, v118, v140
	v_mfma_f32_32x32x16_bf16 v[0:15], v[182:185], v[144:147], v[0:15]
	v_add_f32_e32 v140, v119, v140
	v_add_f32_e32 v140, v120, v140
	v_add_f32_e32 v140, v121, v140
	v_add_f32_e32 v140, v122, v140
	v_add_f32_e32 v140, v123, v140
	v_add_f32_e32 v140, v124, v140
	v_add_f32_e32 v140, v125, v140
	v_mfma_f32_32x32x16_bf16 v[48:63], v[182:185], v[186:189], v[48:63]
	v_add_f32_e32 v140, v126, v140
	v_add_f32_e32 v165, v127, v140
	v_cvt_pk_bf16_f32 v144, v112, v113
	v_cvt_pk_bf16_f32 v145, v114, v115
	v_cvt_pk_bf16_f32 v146, v116, v117
	v_cvt_pk_bf16_f32 v147, v118, v119
	v_cvt_pk_bf16_f32 v140, v120, v121
	v_mfma_f32_32x32x16_bf16 v[32:47], v[182:185], v[214:217], v[32:47]
	v_cvt_pk_bf16_f32 v141, v122, v123
	v_cvt_pk_bf16_f32 v142, v124, v125
	v_cvt_pk_bf16_f32 v143, v126, v127
	v_mfma_f32_32x32x16_bf16 v[16:31], v[182:185], v[218:221], v[16:31]
	s_waitcnt vmcnt(3)
	s_waitcnt lgkmcnt(0)
	s_barrier
	v_mfma_f32_32x32x16_bf16 v[0:15], v[160:163], v[222:225], v[0:15]
	v_mfma_f32_32x32x16_bf16 v[48:63], v[160:163], v[226:229], v[48:63]
	v_mfma_f32_32x32x16_bf16 v[32:47], v[160:163], v[230:233], v[32:47]
	v_mfma_f32_32x32x16_bf16 v[16:31], v[160:163], v[234:237], v[16:31]
	v_add_u32_e32 v208, s101, v208
	v_add_u32_e32 v209, s101, v209
	v_add_u32_e32 v210, s101, v210
	v_add_u32_e32 v211, s101, v211
	ds_read_b128 v[160:163], v208 offset:32768
	ds_read_b128 v[132:135], v209 offset:32768
	ds_read_b128 v[182:185], v210 offset:32768
	ds_read_b128 v[188:191], v211 offset:32768
	ds_read_b128 v[222:225], v208 offset:36864
	ds_read_b128 v[226:229], v209 offset:36864
	ds_read_b128 v[238:241], v210 offset:36864
	ds_read_b128 v[242:245], v211 offset:36864
	v_exp_f32_e32 v166, v84
	v_exp_f32_e32 v167, v85
	s_waitcnt lgkmcnt(7)
	v_mfma_f32_32x32x16_bf16 v[112:127], v[160:163], v[64:67], v[96:111]
	v_exp_f32_e32 v186, v90
	v_exp_f32_e32 v187, v91
	s_andn2_b64 s[0:1], s[6:7], exec
	s_and_b64 s[6:7], s[8:9], exec
	s_or_b64 s[6:7], s[0:1], s[6:7]
	s_waitcnt lgkmcnt(6)
	v_mfma_f32_32x32x16_bf16 v[112:127], v[132:135], v[68:71], v[112:127]
	v_exp_f32_e32 v160, v80
	v_exp_f32_e32 v161, v81
	v_exp_f32_e32 v162, v82
	v_exp_f32_e32 v163, v83
	v_add_f32_e32 v80, v160, v165
	v_add_f32_e32 v80, v161, v80
	v_add_f32_e32 v165, v162, v80
	s_waitcnt lgkmcnt(5)
	v_mfma_f32_32x32x16_bf16 v[112:127], v[182:185], v[72:75], v[112:127]
	v_exp_f32_e32 v182, v86
	v_exp_f32_e32 v183, v87
	v_exp_f32_e32 v184, v88
	v_exp_f32_e32 v185, v89
	v_add_f32_e32 v165, v163, v165
	v_add_f32_e32 v165, v166, v165
	v_add_f32_e32 v165, v167, v165
	s_waitcnt lgkmcnt(4)
	v_mfma_f32_32x32x16_bf16 v[112:127], v[188:191], v[76:79], v[112:127]
	v_exp_f32_e32 v188, v92
	v_exp_f32_e32 v189, v93
	v_exp_f32_e32 v190, v94
	v_exp_f32_e32 v191, v95
	v_add_f32_e32 v165, v182, v165
	v_add_f32_e32 v165, v183, v165
	v_add_f32_e32 v165, v184, v165
	s_waitcnt lgkmcnt(3)
	v_mfma_f32_32x32x16_bf16 v[80:95], v[222:225], v[64:67], v[96:111]
	v_add_f32_e32 v165, v185, v165
	v_add_f32_e32 v165, v186, v165
	v_add_f32_e32 v165, v187, v165
	v_add_f32_e32 v165, v188, v165
	v_add_f32_e32 v165, v189, v165
	v_add_f32_e32 v165, v190, v165
	v_add_f32_e32 v165, v191, v165
	s_waitcnt lgkmcnt(2)
	v_mfma_f32_32x32x16_bf16 v[80:95], v[226:229], v[68:71], v[80:95]
	v_mov_b32_e32 v179, v165
	s_nop 1
	v_permlane32_swap_b32_e32 v165, v179
	v_add_f32_e64 v178, v164, v178
	v_add_f32_e64 v179, v165, v179
	v_cmp_ge_f32_e32 vcc, s99, v179
	s_cmp_eq_u64 vcc, exec
	s_waitcnt lgkmcnt(1)
	v_mfma_f32_32x32x16_bf16 v[80:95], v[238:241], v[72:75], v[80:95]
	s_waitcnt lgkmcnt(0)
	v_mfma_f32_32x32x16_bf16 v[80:95], v[242:245], v[76:79], v[80:95]
	s_cbranch_scc0 .LBB0_408
